# B3 decode rows pipelined; final-norm gain vector loaded once per wave
# speedup vs baseline: 1.1611x; 1.0035x over previous
.LBB0_73:
	s_mov_b64 s[28:29], -1
	s_mov_b64 s[0:1], 0
	s_cmp_lt_i32 s72, 21
	s_mov_b64 s[20:21], 0
	s_cbranch_scc1 .LBB0_80
	s_cmp_eq_u32 s72, 21
	s_mov_b64 s[20:21], -1
	s_cbranch_scc0 .LBB0_84
	v_mov_b32_e32 v2, v133
	v_readlane_b32 s20, v214, 63
	v_ashrrev_i32_e32 v0, 6, v2
	v_readlane_b32 s21, v213, 0
	v_add_u32_e32 v20, s20, v0
	v_cmp_gt_i32_e32 vcc, s69, v20
	s_and_saveexec_b64 s[20:21], vcc
	s_cbranch_execz .LBB0_83
	s_waitcnt lgkmcnt(0)
	v_lshlrev_b32_e32 v1, 4, v2
	v_readlane_b32 s22, v214, 63
	v_and_b32_e32 v64, 0x3f0, v1
	v_ashrrev_i32_e32 v1, 31, v0
	v_readlane_b32 s23, v213, 0
	v_and_b32_e32 v2, 63, v2
	v_lshl_add_u64 v[16:17], s[90:91], 0, v[64:65]
	v_lshl_add_u64 v[0:1], s[22:23], 0, v[0:1]
	v_lshlrev_b64 v[0:1], 12, v[0:1]
	v_readlane_b32 s22, v214, 61
	v_lshl_or_b32 v0, v2, 4, v0
	v_readlane_b32 s23, v214, 62
	s_mov_b64 s[28:29], 0
	s_nop 0
	v_lshl_add_u64 v[18:19], s[22:23], 0, v[0:1]
	global_load_dwordx4 v[150:153], v[16:17], off
	global_load_dwordx4 v[154:157], v[16:17], off offset:1024
	global_load_dwordx4 v[158:161], v[16:17], off offset:2048
	global_load_dwordx4 v[162:165], v[16:17], off offset:3072
	s_branch .LBB0_78

.LBB0_78:
	global_load_dwordx4 v[12:15], v[18:19], off offset:-3072
	global_load_dwordx4 v[8:11], v[18:19], off offset:-2048
	global_load_dwordx4 v[4:7], v[18:19], off offset:-1024
	global_load_dwordx4 v[0:3], v[18:19], off
	v_mov_b32_e32 v21, v65
	v_mov_b32_e32 v22, v65
	v_readlane_b32 s22, v215, 20
	v_readlane_b32 s23, v215, 21
	s_andn2_b64 vcc, exec, s[22:23]
	s_waitcnt vmcnt(0)
	v_mul_f32_e32 v23, v13, v13
	s_waitcnt vmcnt(2)
	v_mul_f32_e32 v24, v9, v9
	s_waitcnt vmcnt(1)
	v_mul_f32_e32 v25, v5, v5
	v_fmac_f32_e32 v23, v12, v12
	v_fmac_f32_e32 v24, v8, v8
	s_waitcnt vmcnt(0)
	v_mul_f32_e32 v26, v1, v1
	v_fmac_f32_e32 v25, v4, v4
	v_fmac_f32_e32 v23, v14, v14
	v_fmac_f32_e32 v24, v10, v10
	v_fmac_f32_e32 v26, v0, v0
	v_fmac_f32_e32 v25, v6, v6
	v_fmac_f32_e32 v23, v15, v15
	v_fmac_f32_e32 v24, v11, v11
	v_fmac_f32_e32 v26, v2, v2
	v_fmac_f32_e32 v25, v7, v7
	v_add_f32_e32 v23, v23, v24
	v_fmac_f32_e32 v26, v3, v3
	v_add_f32_e32 v23, v23, v25
	v_add_f32_e32 v23, v23, v26
	s_nop 1
	v_add_f32_dpp v23, v23, v23 quad_perm:[1,0,3,2] row_mask:0xf bank_mask:0xf bound_ctrl:1
	s_nop 1
	v_add_f32_dpp v23, v23, v23 quad_perm:[2,3,0,1] row_mask:0xf bank_mask:0xf bound_ctrl:1
	s_nop 1
	v_add_f32_dpp v23, v23, v23 row_half_mirror row_mask:0xf bank_mask:0xf bound_ctrl:1
	s_nop 1
	v_add_f32_dpp v23, v23, v23 row_mirror row_mask:0xf bank_mask:0xf bound_ctrl:1
	s_nop 1
	v_mov_b32_dpp v21, v23 row_bcast:15 row_mask:0xa bank_mask:0xf
	v_add_f32_e32 v21, v23, v21
	s_nop 1
	v_mov_b32_dpp v22, v21 row_bcast:31 row_mask:0xc bank_mask:0xf
	v_add_f32_e32 v21, v21, v22
	s_nop 0
	v_readlane_b32 s2, v21, 63
	s_cbranch_vccnz .LBB0_77
	v_fma_f32 v21, s2, v191, v188
	v_mul_f32_e32 v26, 0x4b800000, v21
	v_cmp_gt_f32_e32 vcc, s82, v21
	s_nop 1
	v_cndmask_b32_e32 v21, v21, v26, vcc
	v_rsq_f32_e32 v21, v21
	s_nop 0
	v_mul_f32_e32 v26, 0x45800000, v21
	v_cndmask_b32_e32 v26, v21, v26, vcc
	v_pk_mul_f32 v[12:13], v[12:13], v[26:27] op_sel_hi:[1,0]
	v_pk_mul_f32 v[14:15], v[14:15], v[26:27] op_sel_hi:[1,0]
	v_pk_mul_f32 v[10:11], v[10:11], v[26:27] op_sel_hi:[1,0]
	v_pk_mul_f32 v[8:9], v[8:9], v[26:27] op_sel_hi:[1,0]
	v_pk_mul_f32 v[6:7], v[6:7], v[26:27] op_sel_hi:[1,0]
	v_pk_mul_f32 v[4:5], v[4:5], v[26:27] op_sel_hi:[1,0]
	v_pk_mul_f32 v[2:3], v[2:3], v[26:27] op_sel_hi:[1,0]
	v_pk_mul_f32 v[0:1], v[0:1], v[26:27] op_sel_hi:[1,0]
	v_pk_mul_f32 v[14:15], v[14:15], v[152:153]
	v_pk_mul_f32 v[12:13], v[12:13], v[150:151]
	global_store_dwordx4 v[18:19], v[12:15], off offset:-3072
	v_pk_mul_f32 v[8:9], v[8:9], v[154:155]
	v_pk_mul_f32 v[10:11], v[10:11], v[156:157]
	global_store_dwordx4 v[18:19], v[8:11], off offset:-2048
	v_pk_mul_f32 v[4:5], v[4:5], v[158:159]
	v_pk_mul_f32 v[6:7], v[6:7], v[160:161]
	global_store_dwordx4 v[18:19], v[4:7], off offset:-1024
	v_pk_mul_f32 v[0:1], v[0:1], v[162:163]
	v_pk_mul_f32 v[2:3], v[2:3], v[164:165]
	global_store_dwordx4 v[18:19], v[0:3], off
	s_branch .LBB0_77

.LBB0_213:
	v_lshrrev_b32_e32 v170, 6, v133
	v_and_b32_e32 v171, 63, v133
	v_lshlrev_b32_e32 v172, 4, v170
	v_add_u32_e32 v172, 0x19110000, v172
	v_lshlrev_b32_e32 v173, 6, v170
	v_add_u32_e32 v173, v173, v171
	v_lshlrev_b32_e32 v174, 2, v173
	v_add_u32_e32 v174, 0x19314000, v174
	v_lshlrev_b32_e32 v175, 1, v173
	v_add_u32_e32 v176, 0x4580200, v175
	v_add_u32_e32 v175, 0x6a01100, v175
	v_mul_u32_u24_e32 v177, 0x600, v170
	v_lshl_add_u32 v177, v171, 2, v177
	v_add_u32_e32 v177, 0xcf90500, v177
	v_readlane_b32 s20, v214, 20
	s_add_i32 s28, s20, 0x4000
	s_add_i32 s0, s28, 0
	s_lshl_b32 s1, s0, 7
	v_add_u32_e32 v107, s1, v172
	global_load_dwordx4 v[100:103], v107, s[94:95]
	s_mul_i32 s1, s0, 0x3000
	v_add_u32_e32 v107, s1, v177
	global_load_dword v104, v107, s[94:95]
	s_lshl_b32 s1, s0, 11
	v_add_u32_e32 v107, s1, v174
	global_load_dword v105, v107, s[94:95]
	s_mul_i32 s1, s0, 0x1900
	v_add_u32_e32 v107, s1, v175
	global_load_ushort v106, v107, s[94:95]
	s_add_i32 s0, s28, 1
	s_lshl_b32 s1, s0, 7
	v_add_u32_e32 v115, s1, v172
	global_load_dwordx4 v[108:111], v115, s[94:95]
	s_mul_i32 s1, s0, 0x3000
	v_add_u32_e32 v115, s1, v177
	global_load_dword v112, v115, s[94:95]
	s_lshl_b32 s1, s0, 11
	v_add_u32_e32 v115, s1, v174
	global_load_dword v113, v115, s[94:95]
	s_mul_i32 s1, s0, 0x1900
	v_add_u32_e32 v115, s1, v175
	global_load_ushort v114, v115, s[94:95]
	s_add_i32 s0, s28, 2
	s_lshl_b32 s1, s0, 7
	v_add_u32_e32 v123, s1, v172
	global_load_dwordx4 v[116:119], v123, s[94:95]
	s_mul_i32 s1, s0, 0x3000
	v_add_u32_e32 v123, s1, v177
	global_load_dword v120, v123, s[94:95]
	s_lshl_b32 s1, s0, 11
	v_add_u32_e32 v123, s1, v174
	global_load_dword v121, v123, s[94:95]
	s_mul_i32 s1, s0, 0x1900
	v_add_u32_e32 v123, s1, v175
	global_load_ushort v122, v123, s[94:95]
	s_add_i32 s0, s28, 3
	s_lshl_b32 s1, s0, 7
	v_add_u32_e32 v131, s1, v172
	global_load_dwordx4 v[124:127], v131, s[94:95]
	s_mul_i32 s1, s0, 0x3000
	v_add_u32_e32 v131, s1, v177
	global_load_dword v128, v131, s[94:95]
	s_lshl_b32 s1, s0, 11
	v_add_u32_e32 v131, s1, v174
	global_load_dword v129, v131, s[94:95]
	s_mul_i32 s1, s0, 0x1900
	v_add_u32_e32 v131, s1, v175
	global_load_ushort v130, v131, s[94:95]
	s_add_i32 s0, s28, 4
	s_lshl_b32 s1, s0, 7
	v_add_u32_e32 v141, s1, v172
	global_load_dwordx4 v[134:137], v141, s[94:95]
	s_mul_i32 s1, s0, 0x3000
	v_add_u32_e32 v141, s1, v177
	global_load_dword v138, v141, s[94:95]
	s_lshl_b32 s1, s0, 11
	v_add_u32_e32 v141, s1, v174
	global_load_dword v139, v141, s[94:95]
	s_mul_i32 s1, s0, 0x1900
	v_add_u32_e32 v141, s1, v175
	global_load_ushort v140, v141, s[94:95]
	s_add_i32 s0, s28, 5
	s_lshl_b32 s1, s0, 7
	v_add_u32_e32 v149, s1, v172
	global_load_dwordx4 v[142:145], v149, s[94:95]
	s_mul_i32 s1, s0, 0x3000
	v_add_u32_e32 v149, s1, v177
	global_load_dword v146, v149, s[94:95]
	s_lshl_b32 s1, s0, 11
	v_add_u32_e32 v149, s1, v174
	global_load_dword v147, v149, s[94:95]
	s_mul_i32 s1, s0, 0x1900
	v_add_u32_e32 v149, s1, v175
	global_load_ushort v148, v149, s[94:95]
	s_add_i32 s0, s28, 6
	s_lshl_b32 s1, s0, 7
	v_add_u32_e32 v157, s1, v172
	global_load_dwordx4 v[150:153], v157, s[94:95]
	s_mul_i32 s1, s0, 0x3000
	v_add_u32_e32 v157, s1, v177
	global_load_dword v154, v157, s[94:95]
	s_lshl_b32 s1, s0, 11
	v_add_u32_e32 v157, s1, v174
	global_load_dword v155, v157, s[94:95]
	s_mul_i32 s1, s0, 0x1900
	v_add_u32_e32 v157, s1, v175
	global_load_ushort v156, v157, s[94:95]
	s_add_i32 s0, s28, 7
	s_lshl_b32 s1, s0, 7
	v_add_u32_e32 v165, s1, v172
	global_load_dwordx4 v[158:161], v165, s[94:95]
	s_mul_i32 s1, s0, 0x3000
	v_add_u32_e32 v165, s1, v177
	global_load_dword v162, v165, s[94:95]
	s_lshl_b32 s1, s0, 11
	v_add_u32_e32 v165, s1, v174
	global_load_dword v163, v165, s[94:95]
	s_mul_i32 s1, s0, 0x1900
	v_add_u32_e32 v165, s1, v175
	global_load_ushort v164, v165, s[94:95]
	s_waitcnt vmcnt(16)
	v_fmac_f32_e32 v105, v102, v104
	v_fmac_f32_e32 v113, v110, v112
	v_fmac_f32_e32 v121, v118, v120
	v_fmac_f32_e32 v129, v126, v128
	v_add_f32_dpp v178, v105, v105 quad_perm:[1,0,3,2] row_mask:0xf bank_mask:0xf bound_ctrl:1
	v_add_f32_dpp v179, v113, v113 quad_perm:[1,0,3,2] row_mask:0xf bank_mask:0xf bound_ctrl:1
	v_add_f32_dpp v180, v121, v121 quad_perm:[1,0,3,2] row_mask:0xf bank_mask:0xf bound_ctrl:1
	v_add_f32_dpp v181, v129, v129 quad_perm:[1,0,3,2] row_mask:0xf bank_mask:0xf bound_ctrl:1
	v_add_f32_dpp v178, v178, v178 quad_perm:[2,3,0,1] row_mask:0xf bank_mask:0xf bound_ctrl:1
	v_add_f32_dpp v179, v179, v179 quad_perm:[2,3,0,1] row_mask:0xf bank_mask:0xf bound_ctrl:1
	v_add_f32_dpp v180, v180, v180 quad_perm:[2,3,0,1] row_mask:0xf bank_mask:0xf bound_ctrl:1
	v_add_f32_dpp v181, v181, v181 quad_perm:[2,3,0,1] row_mask:0xf bank_mask:0xf bound_ctrl:1
	v_add_f32_dpp v178, v178, v178 row_half_mirror row_mask:0xf bank_mask:0xf bound_ctrl:1
	v_add_f32_dpp v179, v179, v179 row_half_mirror row_mask:0xf bank_mask:0xf bound_ctrl:1
	v_add_f32_dpp v180, v180, v180 row_half_mirror row_mask:0xf bank_mask:0xf bound_ctrl:1
	v_add_f32_dpp v181, v181, v181 row_half_mirror row_mask:0xf bank_mask:0xf bound_ctrl:1
	v_add_f32_dpp v178, v178, v178 row_mirror row_mask:0xf bank_mask:0xf bound_ctrl:1
	v_add_f32_dpp v179, v179, v179 row_mirror row_mask:0xf bank_mask:0xf bound_ctrl:1
	v_add_f32_dpp v180, v180, v180 row_mirror row_mask:0xf bank_mask:0xf bound_ctrl:1
	v_add_f32_dpp v181, v181, v181 row_mirror row_mask:0xf bank_mask:0xf bound_ctrl:1
	v_mov_b32_e32 v182, v65
	v_mov_b32_e32 v183, v65
	v_mov_b32_e32 v184, v65
	v_mov_b32_e32 v185, v65
	v_mov_b32_dpp v182, v178 row_bcast:15 row_mask:0xa bank_mask:0xf
	v_mov_b32_dpp v183, v179 row_bcast:15 row_mask:0xa bank_mask:0xf
	v_mov_b32_dpp v184, v180 row_bcast:15 row_mask:0xa bank_mask:0xf
	v_mov_b32_dpp v185, v181 row_bcast:15 row_mask:0xa bank_mask:0xf
	v_add_f32_e32 v178, v178, v182
	v_add_f32_e32 v179, v179, v183
	v_add_f32_e32 v180, v180, v184
	v_add_f32_e32 v181, v181, v185
	v_mov_b32_e32 v182, v65
	v_mov_b32_e32 v183, v65
	v_mov_b32_e32 v184, v65
	v_mov_b32_e32 v185, v65
	v_mov_b32_dpp v182, v178 row_bcast:31 row_mask:0xc bank_mask:0xf
	v_mov_b32_dpp v183, v179 row_bcast:31 row_mask:0xc bank_mask:0xf
	v_mov_b32_dpp v184, v180 row_bcast:31 row_mask:0xc bank_mask:0xf
	v_mov_b32_dpp v185, v181 row_bcast:31 row_mask:0xc bank_mask:0xf
	v_add_f32_e32 v178, v178, v182
	v_add_f32_e32 v179, v179, v183
	v_add_f32_e32 v180, v180, v184
	v_add_f32_e32 v181, v181, v185
	v_readlane_b32 s0, v178, 63
	v_readlane_b32 s1, v179, 63
	v_readlane_b32 s2, v180, 63
	v_readlane_b32 s20, v181, 63
	v_lshlrev_b32_e32 v106, 16, v106
	v_lshlrev_b32_e32 v114, 16, v114
	v_lshlrev_b32_e32 v122, 16, v122
	v_lshlrev_b32_e32 v130, 16, v130
	v_fmac_f32_e32 v105, s0, v193
	v_fmac_f32_e32 v113, s1, v193
	v_fmac_f32_e32 v121, s2, v193
	v_fmac_f32_e32 v129, s20, v193
	v_mul_f32_e32 v178, v105, v105
	v_mul_f32_e32 v179, v113, v113
	v_mul_f32_e32 v180, v121, v121
	v_mul_f32_e32 v181, v129, v129
	v_mov_b32_e32 v182, v65
	v_mov_b32_e32 v183, v65
	v_mov_b32_e32 v184, v65
	v_mov_b32_e32 v185, v65
	v_mov_b32_dpp v182, v178 quad_perm:[1,0,3,2] row_mask:0xf bank_mask:0xf
	v_mov_b32_dpp v183, v179 quad_perm:[1,0,3,2] row_mask:0xf bank_mask:0xf
	v_mov_b32_dpp v184, v180 quad_perm:[1,0,3,2] row_mask:0xf bank_mask:0xf
	v_mov_b32_dpp v185, v181 quad_perm:[1,0,3,2] row_mask:0xf bank_mask:0xf
	v_fmac_f32_e32 v182, v105, v105
	v_fmac_f32_e32 v183, v113, v113
	v_fmac_f32_e32 v184, v121, v121
	v_fmac_f32_e32 v185, v129, v129
	v_mov_b32_e32 v178, v182
	v_mov_b32_e32 v179, v183
	v_mov_b32_e32 v180, v184
	v_mov_b32_e32 v181, v185
	v_add_f32_dpp v178, v178, v178 quad_perm:[2,3,0,1] row_mask:0xf bank_mask:0xf bound_ctrl:1
	v_add_f32_dpp v179, v179, v179 quad_perm:[2,3,0,1] row_mask:0xf bank_mask:0xf bound_ctrl:1
	v_add_f32_dpp v180, v180, v180 quad_perm:[2,3,0,1] row_mask:0xf bank_mask:0xf bound_ctrl:1
	v_add_f32_dpp v181, v181, v181 quad_perm:[2,3,0,1] row_mask:0xf bank_mask:0xf bound_ctrl:1
	v_add_f32_dpp v178, v178, v178 row_half_mirror row_mask:0xf bank_mask:0xf bound_ctrl:1
	v_add_f32_dpp v179, v179, v179 row_half_mirror row_mask:0xf bank_mask:0xf bound_ctrl:1
	v_add_f32_dpp v180, v180, v180 row_half_mirror row_mask:0xf bank_mask:0xf bound_ctrl:1
	v_add_f32_dpp v181, v181, v181 row_half_mirror row_mask:0xf bank_mask:0xf bound_ctrl:1
	v_add_f32_dpp v178, v178, v178 row_mirror row_mask:0xf bank_mask:0xf bound_ctrl:1
	v_add_f32_dpp v179, v179, v179 row_mirror row_mask:0xf bank_mask:0xf bound_ctrl:1
	v_add_f32_dpp v180, v180, v180 row_mirror row_mask:0xf bank_mask:0xf bound_ctrl:1
	v_add_f32_dpp v181, v181, v181 row_mirror row_mask:0xf bank_mask:0xf bound_ctrl:1
	v_mov_b32_e32 v182, v65
	v_mov_b32_e32 v183, v65
	v_mov_b32_e32 v184, v65
	v_mov_b32_e32 v185, v65
	v_mov_b32_dpp v182, v178 row_bcast:15 row_mask:0xa bank_mask:0xf
	v_mov_b32_dpp v183, v179 row_bcast:15 row_mask:0xa bank_mask:0xf
	v_mov_b32_dpp v184, v180 row_bcast:15 row_mask:0xa bank_mask:0xf
	v_mov_b32_dpp v185, v181 row_bcast:15 row_mask:0xa bank_mask:0xf
	v_add_f32_e32 v178, v178, v182
	v_add_f32_e32 v179, v179, v183
	v_add_f32_e32 v180, v180, v184
	v_add_f32_e32 v181, v181, v185
	v_mov_b32_e32 v182, v65
	v_mov_b32_e32 v183, v65
	v_mov_b32_e32 v184, v65
	v_mov_b32_e32 v185, v65
	v_mov_b32_dpp v182, v178 row_bcast:31 row_mask:0xc bank_mask:0xf
	v_mov_b32_dpp v183, v179 row_bcast:31 row_mask:0xc bank_mask:0xf
	v_mov_b32_dpp v184, v180 row_bcast:31 row_mask:0xc bank_mask:0xf
	v_mov_b32_dpp v185, v181 row_bcast:31 row_mask:0xc bank_mask:0xf
	v_add_f32_e32 v178, v178, v182
	v_add_f32_e32 v179, v179, v183
	v_add_f32_e32 v180, v180, v184
	v_add_f32_e32 v181, v181, v185
	v_readlane_b32 s0, v178, 63
	v_readlane_b32 s1, v179, 63
	v_readlane_b32 s2, v180, 63
	v_readlane_b32 s20, v181, 63
	v_mul_f32_e32 v182, 0xbfb8aa3b, v106
	v_mul_f32_e32 v183, 0xbfb8aa3b, v114
	v_mul_f32_e32 v184, 0xbfb8aa3b, v122
	v_mul_f32_e32 v185, 0xbfb8aa3b, v130
	v_fma_f32 v178, s0, v194, v189
	v_fma_f32 v179, s1, v194, v189
	v_fma_f32 v180, s2, v194, v189
	v_fma_f32 v181, s20, v194, v189
	v_exp_f32_e32 v182, v182
	v_exp_f32_e32 v183, v183
	v_exp_f32_e32 v184, v184
	v_exp_f32_e32 v185, v185
	v_rsq_f32_e32 v178, v178
	v_rsq_f32_e32 v179, v179
	v_rsq_f32_e32 v180, v180
	v_rsq_f32_e32 v181, v181
	v_add_f32_e32 v182, 1.0, v182
	v_add_f32_e32 v183, 1.0, v183
	v_add_f32_e32 v184, 1.0, v184
	v_add_f32_e32 v185, 1.0, v185
	v_mul_f32_e32 v178, v105, v178
	v_mul_f32_e32 v179, v113, v179
	v_mul_f32_e32 v180, v121, v180
	v_mul_f32_e32 v181, v129, v181
	v_rcp_f32_e32 v182, v182
	v_rcp_f32_e32 v183, v183
	v_rcp_f32_e32 v184, v184
	v_rcp_f32_e32 v185, v185
	v_fma_f32 v178, v42, v178, v43
	v_fma_f32 v179, v42, v179, v43
	v_fma_f32 v180, v42, v180, v43
	v_fma_f32 v181, v42, v181, v43
	v_fmac_f32_e32 v178, v100, v104
	v_fmac_f32_e32 v179, v108, v112
	v_fmac_f32_e32 v180, v116, v120
	v_fmac_f32_e32 v181, v124, v128
	v_mul_f32_e32 v182, v182, v106
	v_mul_f32_e32 v183, v183, v114
	v_mul_f32_e32 v184, v184, v122
	v_mul_f32_e32 v185, v185, v130
	v_mul_f32_e32 v178, v182, v178
	v_mul_f32_e32 v179, v183, v179
	v_mul_f32_e32 v180, v184, v180
	v_mul_f32_e32 v181, v185, v181
	v_bfe_u32 v182, v178, 16, 1
	v_bfe_u32 v183, v179, 16, 1
	v_bfe_u32 v184, v180, 16, 1
	v_bfe_u32 v185, v181, 16, 1
	v_add3_u32 v178, v178, v182, s27
	v_add3_u32 v179, v179, v183, s27
	v_add3_u32 v180, v180, v184, s27
	v_add3_u32 v181, v181, v185, s27
	s_add_i32 s0, s28, 0
	s_lshl_b32 s0, s0, 11
	v_add_u32_e32 v182, s0, v176
	s_add_i32 s0, s28, 1
	s_lshl_b32 s0, s0, 11
	v_add_u32_e32 v183, s0, v176
	s_add_i32 s0, s28, 2
	s_lshl_b32 s0, s0, 11
	v_add_u32_e32 v184, s0, v176
	s_add_i32 s0, s28, 3
	s_lshl_b32 s0, s0, 11
	v_add_u32_e32 v185, s0, v176
	global_store_short_d16_hi v182, v178, s[94:95]
	global_store_short_d16_hi v183, v179, s[94:95]
	global_store_short_d16_hi v184, v180, s[94:95]
	global_store_short_d16_hi v185, v181, s[94:95]
	s_add_i32 s0, s28, 8
	s_lshl_b32 s1, s0, 7
	v_add_u32_e32 v107, s1, v172
	global_load_dwordx4 v[100:103], v107, s[94:95]
	s_mul_i32 s1, s0, 0x3000
	v_add_u32_e32 v107, s1, v177
	global_load_dword v104, v107, s[94:95]
	s_lshl_b32 s1, s0, 11
	v_add_u32_e32 v107, s1, v174
	global_load_dword v105, v107, s[94:95]
	s_mul_i32 s1, s0, 0x1900
	v_add_u32_e32 v107, s1, v175
	global_load_ushort v106, v107, s[94:95]
	s_add_i32 s0, s28, 9
	s_lshl_b32 s1, s0, 7
	v_add_u32_e32 v115, s1, v172
	global_load_dwordx4 v[108:111], v115, s[94:95]
	s_mul_i32 s1, s0, 0x3000
	v_add_u32_e32 v115, s1, v177
	global_load_dword v112, v115, s[94:95]
	s_lshl_b32 s1, s0, 11
	v_add_u32_e32 v115, s1, v174
	global_load_dword v113, v115, s[94:95]
	s_mul_i32 s1, s0, 0x1900
	v_add_u32_e32 v115, s1, v175
	global_load_ushort v114, v115, s[94:95]
	s_add_i32 s0, s28, 10
	s_lshl_b32 s1, s0, 7
	v_add_u32_e32 v123, s1, v172
	global_load_dwordx4 v[116:119], v123, s[94:95]
	s_mul_i32 s1, s0, 0x3000
	v_add_u32_e32 v123, s1, v177
	global_load_dword v120, v123, s[94:95]
	s_lshl_b32 s1, s0, 11
	v_add_u32_e32 v123, s1, v174
	global_load_dword v121, v123, s[94:95]
	s_mul_i32 s1, s0, 0x1900
	v_add_u32_e32 v123, s1, v175
	global_load_ushort v122, v123, s[94:95]
	s_add_i32 s0, s28, 11
	s_lshl_b32 s1, s0, 7
	v_add_u32_e32 v131, s1, v172
	global_load_dwordx4 v[124:127], v131, s[94:95]
	s_mul_i32 s1, s0, 0x3000
	v_add_u32_e32 v131, s1, v177
	global_load_dword v128, v131, s[94:95]
	s_lshl_b32 s1, s0, 11
	v_add_u32_e32 v131, s1, v174
	global_load_dword v129, v131, s[94:95]
	s_mul_i32 s1, s0, 0x1900
	v_add_u32_e32 v131, s1, v175
	global_load_ushort v130, v131, s[94:95]
	s_waitcnt vmcnt(16)
	v_fmac_f32_e32 v139, v136, v138
	v_fmac_f32_e32 v147, v144, v146
	v_fmac_f32_e32 v155, v152, v154
	v_fmac_f32_e32 v163, v160, v162
	v_add_f32_dpp v178, v139, v139 quad_perm:[1,0,3,2] row_mask:0xf bank_mask:0xf bound_ctrl:1
	v_add_f32_dpp v179, v147, v147 quad_perm:[1,0,3,2] row_mask:0xf bank_mask:0xf bound_ctrl:1
	v_add_f32_dpp v180, v155, v155 quad_perm:[1,0,3,2] row_mask:0xf bank_mask:0xf bound_ctrl:1
	v_add_f32_dpp v181, v163, v163 quad_perm:[1,0,3,2] row_mask:0xf bank_mask:0xf bound_ctrl:1
	v_add_f32_dpp v178, v178, v178 quad_perm:[2,3,0,1] row_mask:0xf bank_mask:0xf bound_ctrl:1
	v_add_f32_dpp v179, v179, v179 quad_perm:[2,3,0,1] row_mask:0xf bank_mask:0xf bound_ctrl:1
	v_add_f32_dpp v180, v180, v180 quad_perm:[2,3,0,1] row_mask:0xf bank_mask:0xf bound_ctrl:1
	v_add_f32_dpp v181, v181, v181 quad_perm:[2,3,0,1] row_mask:0xf bank_mask:0xf bound_ctrl:1
	v_add_f32_dpp v178, v178, v178 row_half_mirror row_mask:0xf bank_mask:0xf bound_ctrl:1
	v_add_f32_dpp v179, v179, v179 row_half_mirror row_mask:0xf bank_mask:0xf bound_ctrl:1
	v_add_f32_dpp v180, v180, v180 row_half_mirror row_mask:0xf bank_mask:0xf bound_ctrl:1
	v_add_f32_dpp v181, v181, v181 row_half_mirror row_mask:0xf bank_mask:0xf bound_ctrl:1
	v_add_f32_dpp v178, v178, v178 row_mirror row_mask:0xf bank_mask:0xf bound_ctrl:1
	v_add_f32_dpp v179, v179, v179 row_mirror row_mask:0xf bank_mask:0xf bound_ctrl:1
	v_add_f32_dpp v180, v180, v180 row_mirror row_mask:0xf bank_mask:0xf bound_ctrl:1
	v_add_f32_dpp v181, v181, v181 row_mirror row_mask:0xf bank_mask:0xf bound_ctrl:1
	v_mov_b32_e32 v182, v65
	v_mov_b32_e32 v183, v65
	v_mov_b32_e32 v184, v65
	v_mov_b32_e32 v185, v65
	v_mov_b32_dpp v182, v178 row_bcast:15 row_mask:0xa bank_mask:0xf
	v_mov_b32_dpp v183, v179 row_bcast:15 row_mask:0xa bank_mask:0xf
	v_mov_b32_dpp v184, v180 row_bcast:15 row_mask:0xa bank_mask:0xf
	v_mov_b32_dpp v185, v181 row_bcast:15 row_mask:0xa bank_mask:0xf
	v_add_f32_e32 v178, v178, v182
	v_add_f32_e32 v179, v179, v183
	v_add_f32_e32 v180, v180, v184
	v_add_f32_e32 v181, v181, v185
	v_mov_b32_e32 v182, v65
	v_mov_b32_e32 v183, v65
	v_mov_b32_e32 v184, v65
	v_mov_b32_e32 v185, v65
	v_mov_b32_dpp v182, v178 row_bcast:31 row_mask:0xc bank_mask:0xf
	v_mov_b32_dpp v183, v179 row_bcast:31 row_mask:0xc bank_mask:0xf
	v_mov_b32_dpp v184, v180 row_bcast:31 row_mask:0xc bank_mask:0xf
	v_mov_b32_dpp v185, v181 row_bcast:31 row_mask:0xc bank_mask:0xf
	v_add_f32_e32 v178, v178, v182
	v_add_f32_e32 v179, v179, v183
	v_add_f32_e32 v180, v180, v184
	v_add_f32_e32 v181, v181, v185
	v_readlane_b32 s0, v178, 63
	v_readlane_b32 s1, v179, 63
	v_readlane_b32 s2, v180, 63
	v_readlane_b32 s20, v181, 63
	v_lshlrev_b32_e32 v140, 16, v140
	v_lshlrev_b32_e32 v148, 16, v148
	v_lshlrev_b32_e32 v156, 16, v156
	v_lshlrev_b32_e32 v164, 16, v164
	v_fmac_f32_e32 v139, s0, v193
	v_fmac_f32_e32 v147, s1, v193
	v_fmac_f32_e32 v155, s2, v193
	v_fmac_f32_e32 v163, s20, v193
	v_mul_f32_e32 v178, v139, v139
	v_mul_f32_e32 v179, v147, v147
	v_mul_f32_e32 v180, v155, v155
	v_mul_f32_e32 v181, v163, v163
	v_mov_b32_e32 v182, v65
	v_mov_b32_e32 v183, v65
	v_mov_b32_e32 v184, v65
	v_mov_b32_e32 v185, v65
	v_mov_b32_dpp v182, v178 quad_perm:[1,0,3,2] row_mask:0xf bank_mask:0xf
	v_mov_b32_dpp v183, v179 quad_perm:[1,0,3,2] row_mask:0xf bank_mask:0xf
	v_mov_b32_dpp v184, v180 quad_perm:[1,0,3,2] row_mask:0xf bank_mask:0xf
	v_mov_b32_dpp v185, v181 quad_perm:[1,0,3,2] row_mask:0xf bank_mask:0xf
	v_fmac_f32_e32 v182, v139, v139
	v_fmac_f32_e32 v183, v147, v147
	v_fmac_f32_e32 v184, v155, v155
	v_fmac_f32_e32 v185, v163, v163
	v_mov_b32_e32 v178, v182
	v_mov_b32_e32 v179, v183
	v_mov_b32_e32 v180, v184
	v_mov_b32_e32 v181, v185
	v_add_f32_dpp v178, v178, v178 quad_perm:[2,3,0,1] row_mask:0xf bank_mask:0xf bound_ctrl:1
	v_add_f32_dpp v179, v179, v179 quad_perm:[2,3,0,1] row_mask:0xf bank_mask:0xf bound_ctrl:1
	v_add_f32_dpp v180, v180, v180 quad_perm:[2,3,0,1] row_mask:0xf bank_mask:0xf bound_ctrl:1
	v_add_f32_dpp v181, v181, v181 quad_perm:[2,3,0,1] row_mask:0xf bank_mask:0xf bound_ctrl:1
	v_add_f32_dpp v178, v178, v178 row_half_mirror row_mask:0xf bank_mask:0xf bound_ctrl:1
	v_add_f32_dpp v179, v179, v179 row_half_mirror row_mask:0xf bank_mask:0xf bound_ctrl:1
	v_add_f32_dpp v180, v180, v180 row_half_mirror row_mask:0xf bank_mask:0xf bound_ctrl:1
	v_add_f32_dpp v181, v181, v181 row_half_mirror row_mask:0xf bank_mask:0xf bound_ctrl:1
	v_add_f32_dpp v178, v178, v178 row_mirror row_mask:0xf bank_mask:0xf bound_ctrl:1
	v_add_f32_dpp v179, v179, v179 row_mirror row_mask:0xf bank_mask:0xf bound_ctrl:1
	v_add_f32_dpp v180, v180, v180 row_mirror row_mask:0xf bank_mask:0xf bound_ctrl:1
	v_add_f32_dpp v181, v181, v181 row_mirror row_mask:0xf bank_mask:0xf bound_ctrl:1
	v_mov_b32_e32 v182, v65
	v_mov_b32_e32 v183, v65
	v_mov_b32_e32 v184, v65
	v_mov_b32_e32 v185, v65
	v_mov_b32_dpp v182, v178 row_bcast:15 row_mask:0xa bank_mask:0xf
	v_mov_b32_dpp v183, v179 row_bcast:15 row_mask:0xa bank_mask:0xf
	v_mov_b32_dpp v184, v180 row_bcast:15 row_mask:0xa bank_mask:0xf
	v_mov_b32_dpp v185, v181 row_bcast:15 row_mask:0xa bank_mask:0xf
	v_add_f32_e32 v178, v178, v182
	v_add_f32_e32 v179, v179, v183
	v_add_f32_e32 v180, v180, v184
	v_add_f32_e32 v181, v181, v185
	v_mov_b32_e32 v182, v65
	v_mov_b32_e32 v183, v65
	v_mov_b32_e32 v184, v65
	v_mov_b32_e32 v185, v65
	v_mov_b32_dpp v182, v178 row_bcast:31 row_mask:0xc bank_mask:0xf
	v_mov_b32_dpp v183, v179 row_bcast:31 row_mask:0xc bank_mask:0xf
	v_mov_b32_dpp v184, v180 row_bcast:31 row_mask:0xc bank_mask:0xf
	v_mov_b32_dpp v185, v181 row_bcast:31 row_mask:0xc bank_mask:0xf
	v_add_f32_e32 v178, v178, v182
	v_add_f32_e32 v179, v179, v183
	v_add_f32_e32 v180, v180, v184
	v_add_f32_e32 v181, v181, v185
	v_readlane_b32 s0, v178, 63
	v_readlane_b32 s1, v179, 63
	v_readlane_b32 s2, v180, 63
	v_readlane_b32 s20, v181, 63
	v_mul_f32_e32 v182, 0xbfb8aa3b, v140
	v_mul_f32_e32 v183, 0xbfb8aa3b, v148
	v_mul_f32_e32 v184, 0xbfb8aa3b, v156
	v_mul_f32_e32 v185, 0xbfb8aa3b, v164
	v_fma_f32 v178, s0, v194, v189
	v_fma_f32 v179, s1, v194, v189
	v_fma_f32 v180, s2, v194, v189
	v_fma_f32 v181, s20, v194, v189
	v_exp_f32_e32 v182, v182
	v_exp_f32_e32 v183, v183
	v_exp_f32_e32 v184, v184
	v_exp_f32_e32 v185, v185
	v_rsq_f32_e32 v178, v178
	v_rsq_f32_e32 v179, v179
	v_rsq_f32_e32 v180, v180
	v_rsq_f32_e32 v181, v181
	v_add_f32_e32 v182, 1.0, v182
	v_add_f32_e32 v183, 1.0, v183
	v_add_f32_e32 v184, 1.0, v184
	v_add_f32_e32 v185, 1.0, v185
	v_mul_f32_e32 v178, v139, v178
	v_mul_f32_e32 v179, v147, v179
	v_mul_f32_e32 v180, v155, v180
	v_mul_f32_e32 v181, v163, v181
	v_rcp_f32_e32 v182, v182
	v_rcp_f32_e32 v183, v183
	v_rcp_f32_e32 v184, v184
	v_rcp_f32_e32 v185, v185
	v_fma_f32 v178, v42, v178, v43
	v_fma_f32 v179, v42, v179, v43
	v_fma_f32 v180, v42, v180, v43
	v_fma_f32 v181, v42, v181, v43
	v_fmac_f32_e32 v178, v134, v138
	v_fmac_f32_e32 v179, v142, v146
	v_fmac_f32_e32 v180, v150, v154
	v_fmac_f32_e32 v181, v158, v162
	v_mul_f32_e32 v182, v182, v140
	v_mul_f32_e32 v183, v183, v148
	v_mul_f32_e32 v184, v184, v156
	v_mul_f32_e32 v185, v185, v164
	v_mul_f32_e32 v178, v182, v178
	v_mul_f32_e32 v179, v183, v179
	v_mul_f32_e32 v180, v184, v180
	v_mul_f32_e32 v181, v185, v181
	v_bfe_u32 v182, v178, 16, 1
	v_bfe_u32 v183, v179, 16, 1
	v_bfe_u32 v184, v180, 16, 1
	v_bfe_u32 v185, v181, 16, 1
	v_add3_u32 v178, v178, v182, s27
	v_add3_u32 v179, v179, v183, s27
	v_add3_u32 v180, v180, v184, s27
	v_add3_u32 v181, v181, v185, s27
	s_add_i32 s0, s28, 4
	s_lshl_b32 s0, s0, 11
	v_add_u32_e32 v182, s0, v176
	s_add_i32 s0, s28, 5
	s_lshl_b32 s0, s0, 11
	v_add_u32_e32 v183, s0, v176
	s_add_i32 s0, s28, 6
	s_lshl_b32 s0, s0, 11
	v_add_u32_e32 v184, s0, v176
	s_add_i32 s0, s28, 7
	s_lshl_b32 s0, s0, 11
	v_add_u32_e32 v185, s0, v176
	global_store_short_d16_hi v182, v178, s[94:95]
	global_store_short_d16_hi v183, v179, s[94:95]
	global_store_short_d16_hi v184, v180, s[94:95]
	global_store_short_d16_hi v185, v181, s[94:95]
	s_add_i32 s0, s28, 12
	s_lshl_b32 s1, s0, 7
	v_add_u32_e32 v141, s1, v172
	global_load_dwordx4 v[134:137], v141, s[94:95]
	s_mul_i32 s1, s0, 0x3000
	v_add_u32_e32 v141, s1, v177
	global_load_dword v138, v141, s[94:95]
	s_lshl_b32 s1, s0, 11
	v_add_u32_e32 v141, s1, v174
	global_load_dword v139, v141, s[94:95]
	s_mul_i32 s1, s0, 0x1900
	v_add_u32_e32 v141, s1, v175
	global_load_ushort v140, v141, s[94:95]
	s_add_i32 s0, s28, 13
	s_lshl_b32 s1, s0, 7
	v_add_u32_e32 v149, s1, v172
	global_load_dwordx4 v[142:145], v149, s[94:95]
	s_mul_i32 s1, s0, 0x3000
	v_add_u32_e32 v149, s1, v177
	global_load_dword v146, v149, s[94:95]
	s_lshl_b32 s1, s0, 11
	v_add_u32_e32 v149, s1, v174
	global_load_dword v147, v149, s[94:95]
	s_mul_i32 s1, s0, 0x1900
	v_add_u32_e32 v149, s1, v175
	global_load_ushort v148, v149, s[94:95]
	s_add_i32 s0, s28, 14
	s_lshl_b32 s1, s0, 7
	v_add_u32_e32 v157, s1, v172
	global_load_dwordx4 v[150:153], v157, s[94:95]
	s_mul_i32 s1, s0, 0x3000
	v_add_u32_e32 v157, s1, v177
	global_load_dword v154, v157, s[94:95]
	s_lshl_b32 s1, s0, 11
	v_add_u32_e32 v157, s1, v174
	global_load_dword v155, v157, s[94:95]
	s_mul_i32 s1, s0, 0x1900
	v_add_u32_e32 v157, s1, v175
	global_load_ushort v156, v157, s[94:95]
	s_add_i32 s0, s28, 15
	s_lshl_b32 s1, s0, 7
	v_add_u32_e32 v165, s1, v172
	global_load_dwordx4 v[158:161], v165, s[94:95]
	s_mul_i32 s1, s0, 0x3000
	v_add_u32_e32 v165, s1, v177
	global_load_dword v162, v165, s[94:95]
	s_lshl_b32 s1, s0, 11
	v_add_u32_e32 v165, s1, v174
	global_load_dword v163, v165, s[94:95]
	s_mul_i32 s1, s0, 0x1900
	v_add_u32_e32 v165, s1, v175
	global_load_ushort v164, v165, s[94:95]
	s_waitcnt vmcnt(16)
	v_fmac_f32_e32 v105, v102, v104
	v_fmac_f32_e32 v113, v110, v112
	v_fmac_f32_e32 v121, v118, v120
	v_fmac_f32_e32 v129, v126, v128
	v_add_f32_dpp v178, v105, v105 quad_perm:[1,0,3,2] row_mask:0xf bank_mask:0xf bound_ctrl:1
	v_add_f32_dpp v179, v113, v113 quad_perm:[1,0,3,2] row_mask:0xf bank_mask:0xf bound_ctrl:1
	v_add_f32_dpp v180, v121, v121 quad_perm:[1,0,3,2] row_mask:0xf bank_mask:0xf bound_ctrl:1
	v_add_f32_dpp v181, v129, v129 quad_perm:[1,0,3,2] row_mask:0xf bank_mask:0xf bound_ctrl:1
	v_add_f32_dpp v178, v178, v178 quad_perm:[2,3,0,1] row_mask:0xf bank_mask:0xf bound_ctrl:1
	v_add_f32_dpp v179, v179, v179 quad_perm:[2,3,0,1] row_mask:0xf bank_mask:0xf bound_ctrl:1
	v_add_f32_dpp v180, v180, v180 quad_perm:[2,3,0,1] row_mask:0xf bank_mask:0xf bound_ctrl:1
	v_add_f32_dpp v181, v181, v181 quad_perm:[2,3,0,1] row_mask:0xf bank_mask:0xf bound_ctrl:1
	v_add_f32_dpp v178, v178, v178 row_half_mirror row_mask:0xf bank_mask:0xf bound_ctrl:1
	v_add_f32_dpp v179, v179, v179 row_half_mirror row_mask:0xf bank_mask:0xf bound_ctrl:1
	v_add_f32_dpp v180, v180, v180 row_half_mirror row_mask:0xf bank_mask:0xf bound_ctrl:1
	v_add_f32_dpp v181, v181, v181 row_half_mirror row_mask:0xf bank_mask:0xf bound_ctrl:1
	v_add_f32_dpp v178, v178, v178 row_mirror row_mask:0xf bank_mask:0xf bound_ctrl:1
	v_add_f32_dpp v179, v179, v179 row_mirror row_mask:0xf bank_mask:0xf bound_ctrl:1
	v_add_f32_dpp v180, v180, v180 row_mirror row_mask:0xf bank_mask:0xf bound_ctrl:1
	v_add_f32_dpp v181, v181, v181 row_mirror row_mask:0xf bank_mask:0xf bound_ctrl:1
	v_mov_b32_e32 v182, v65
	v_mov_b32_e32 v183, v65
	v_mov_b32_e32 v184, v65
	v_mov_b32_e32 v185, v65
	v_mov_b32_dpp v182, v178 row_bcast:15 row_mask:0xa bank_mask:0xf
	v_mov_b32_dpp v183, v179 row_bcast:15 row_mask:0xa bank_mask:0xf
	v_mov_b32_dpp v184, v180 row_bcast:15 row_mask:0xa bank_mask:0xf
	v_mov_b32_dpp v185, v181 row_bcast:15 row_mask:0xa bank_mask:0xf
	v_add_f32_e32 v178, v178, v182
	v_add_f32_e32 v179, v179, v183
	v_add_f32_e32 v180, v180, v184
	v_add_f32_e32 v181, v181, v185
	v_mov_b32_e32 v182, v65
	v_mov_b32_e32 v183, v65
	v_mov_b32_e32 v184, v65
	v_mov_b32_e32 v185, v65
	v_mov_b32_dpp v182, v178 row_bcast:31 row_mask:0xc bank_mask:0xf
	v_mov_b32_dpp v183, v179 row_bcast:31 row_mask:0xc bank_mask:0xf
	v_mov_b32_dpp v184, v180 row_bcast:31 row_mask:0xc bank_mask:0xf
	v_mov_b32_dpp v185, v181 row_bcast:31 row_mask:0xc bank_mask:0xf
	v_add_f32_e32 v178, v178, v182
	v_add_f32_e32 v179, v179, v183
	v_add_f32_e32 v180, v180, v184
	v_add_f32_e32 v181, v181, v185
	v_readlane_b32 s0, v178, 63
	v_readlane_b32 s1, v179, 63
	v_readlane_b32 s2, v180, 63
	v_readlane_b32 s20, v181, 63
	v_lshlrev_b32_e32 v106, 16, v106
	v_lshlrev_b32_e32 v114, 16, v114
	v_lshlrev_b32_e32 v122, 16, v122
	v_lshlrev_b32_e32 v130, 16, v130
	v_fmac_f32_e32 v105, s0, v193
	v_fmac_f32_e32 v113, s1, v193
	v_fmac_f32_e32 v121, s2, v193
	v_fmac_f32_e32 v129, s20, v193
	v_mul_f32_e32 v178, v105, v105
	v_mul_f32_e32 v179, v113, v113
	v_mul_f32_e32 v180, v121, v121
	v_mul_f32_e32 v181, v129, v129
	v_mov_b32_e32 v182, v65
	v_mov_b32_e32 v183, v65
	v_mov_b32_e32 v184, v65
	v_mov_b32_e32 v185, v65
	v_mov_b32_dpp v182, v178 quad_perm:[1,0,3,2] row_mask:0xf bank_mask:0xf
	v_mov_b32_dpp v183, v179 quad_perm:[1,0,3,2] row_mask:0xf bank_mask:0xf
	v_mov_b32_dpp v184, v180 quad_perm:[1,0,3,2] row_mask:0xf bank_mask:0xf
	v_mov_b32_dpp v185, v181 quad_perm:[1,0,3,2] row_mask:0xf bank_mask:0xf
	v_fmac_f32_e32 v182, v105, v105
	v_fmac_f32_e32 v183, v113, v113
	v_fmac_f32_e32 v184, v121, v121
	v_fmac_f32_e32 v185, v129, v129
	v_mov_b32_e32 v178, v182
	v_mov_b32_e32 v179, v183
	v_mov_b32_e32 v180, v184
	v_mov_b32_e32 v181, v185
	v_add_f32_dpp v178, v178, v178 quad_perm:[2,3,0,1] row_mask:0xf bank_mask:0xf bound_ctrl:1
	v_add_f32_dpp v179, v179, v179 quad_perm:[2,3,0,1] row_mask:0xf bank_mask:0xf bound_ctrl:1
	v_add_f32_dpp v180, v180, v180 quad_perm:[2,3,0,1] row_mask:0xf bank_mask:0xf bound_ctrl:1
	v_add_f32_dpp v181, v181, v181 quad_perm:[2,3,0,1] row_mask:0xf bank_mask:0xf bound_ctrl:1
	v_add_f32_dpp v178, v178, v178 row_half_mirror row_mask:0xf bank_mask:0xf bound_ctrl:1
	v_add_f32_dpp v179, v179, v179 row_half_mirror row_mask:0xf bank_mask:0xf bound_ctrl:1
	v_add_f32_dpp v180, v180, v180 row_half_mirror row_mask:0xf bank_mask:0xf bound_ctrl:1
	v_add_f32_dpp v181, v181, v181 row_half_mirror row_mask:0xf bank_mask:0xf bound_ctrl:1
	v_add_f32_dpp v178, v178, v178 row_mirror row_mask:0xf bank_mask:0xf bound_ctrl:1
	v_add_f32_dpp v179, v179, v179 row_mirror row_mask:0xf bank_mask:0xf bound_ctrl:1
	v_add_f32_dpp v180, v180, v180 row_mirror row_mask:0xf bank_mask:0xf bound_ctrl:1
	v_add_f32_dpp v181, v181, v181 row_mirror row_mask:0xf bank_mask:0xf bound_ctrl:1
	v_mov_b32_e32 v182, v65
	v_mov_b32_e32 v183, v65
	v_mov_b32_e32 v184, v65
	v_mov_b32_e32 v185, v65
	v_mov_b32_dpp v182, v178 row_bcast:15 row_mask:0xa bank_mask:0xf
	v_mov_b32_dpp v183, v179 row_bcast:15 row_mask:0xa bank_mask:0xf
	v_mov_b32_dpp v184, v180 row_bcast:15 row_mask:0xa bank_mask:0xf
	v_mov_b32_dpp v185, v181 row_bcast:15 row_mask:0xa bank_mask:0xf
	v_add_f32_e32 v178, v178, v182
	v_add_f32_e32 v179, v179, v183
	v_add_f32_e32 v180, v180, v184
	v_add_f32_e32 v181, v181, v185
	v_mov_b32_e32 v182, v65
	v_mov_b32_e32 v183, v65
	v_mov_b32_e32 v184, v65
	v_mov_b32_e32 v185, v65
	v_mov_b32_dpp v182, v178 row_bcast:31 row_mask:0xc bank_mask:0xf
	v_mov_b32_dpp v183, v179 row_bcast:31 row_mask:0xc bank_mask:0xf
	v_mov_b32_dpp v184, v180 row_bcast:31 row_mask:0xc bank_mask:0xf
	v_mov_b32_dpp v185, v181 row_bcast:31 row_mask:0xc bank_mask:0xf
	v_add_f32_e32 v178, v178, v182
	v_add_f32_e32 v179, v179, v183
	v_add_f32_e32 v180, v180, v184
	v_add_f32_e32 v181, v181, v185
	v_readlane_b32 s0, v178, 63
	v_readlane_b32 s1, v179, 63
	v_readlane_b32 s2, v180, 63
	v_readlane_b32 s20, v181, 63
	v_mul_f32_e32 v182, 0xbfb8aa3b, v106
	v_mul_f32_e32 v183, 0xbfb8aa3b, v114
	v_mul_f32_e32 v184, 0xbfb8aa3b, v122
	v_mul_f32_e32 v185, 0xbfb8aa3b, v130
	v_fma_f32 v178, s0, v194, v189
	v_fma_f32 v179, s1, v194, v189
	v_fma_f32 v180, s2, v194, v189
	v_fma_f32 v181, s20, v194, v189
	v_exp_f32_e32 v182, v182
	v_exp_f32_e32 v183, v183
	v_exp_f32_e32 v184, v184
	v_exp_f32_e32 v185, v185
	v_rsq_f32_e32 v178, v178
	v_rsq_f32_e32 v179, v179
	v_rsq_f32_e32 v180, v180
	v_rsq_f32_e32 v181, v181
	v_add_f32_e32 v182, 1.0, v182
	v_add_f32_e32 v183, 1.0, v183
	v_add_f32_e32 v184, 1.0, v184
	v_add_f32_e32 v185, 1.0, v185
	v_mul_f32_e32 v178, v105, v178
	v_mul_f32_e32 v179, v113, v179
	v_mul_f32_e32 v180, v121, v180
	v_mul_f32_e32 v181, v129, v181
	v_rcp_f32_e32 v182, v182
	v_rcp_f32_e32 v183, v183
	v_rcp_f32_e32 v184, v184
	v_rcp_f32_e32 v185, v185
	v_fma_f32 v178, v42, v178, v43
	v_fma_f32 v179, v42, v179, v43
	v_fma_f32 v180, v42, v180, v43
	v_fma_f32 v181, v42, v181, v43
	v_fmac_f32_e32 v178, v100, v104
	v_fmac_f32_e32 v179, v108, v112
	v_fmac_f32_e32 v180, v116, v120
	v_fmac_f32_e32 v181, v124, v128
	v_mul_f32_e32 v182, v182, v106
	v_mul_f32_e32 v183, v183, v114
	v_mul_f32_e32 v184, v184, v122
	v_mul_f32_e32 v185, v185, v130
	v_mul_f32_e32 v178, v182, v178
	v_mul_f32_e32 v179, v183, v179
	v_mul_f32_e32 v180, v184, v180
	v_mul_f32_e32 v181, v185, v181
	v_bfe_u32 v182, v178, 16, 1
	v_bfe_u32 v183, v179, 16, 1
	v_bfe_u32 v184, v180, 16, 1
	v_bfe_u32 v185, v181, 16, 1
	v_add3_u32 v178, v178, v182, s27
	v_add3_u32 v179, v179, v183, s27
	v_add3_u32 v180, v180, v184, s27
	v_add3_u32 v181, v181, v185, s27
	s_add_i32 s0, s28, 8
	s_lshl_b32 s0, s0, 11
	v_add_u32_e32 v182, s0, v176
	s_add_i32 s0, s28, 9
	s_lshl_b32 s0, s0, 11
	v_add_u32_e32 v183, s0, v176
	s_add_i32 s0, s28, 10
	s_lshl_b32 s0, s0, 11
	v_add_u32_e32 v184, s0, v176
	s_add_i32 s0, s28, 11
	s_lshl_b32 s0, s0, 11
	v_add_u32_e32 v185, s0, v176
	global_store_short_d16_hi v182, v178, s[94:95]
	global_store_short_d16_hi v183, v179, s[94:95]
	global_store_short_d16_hi v184, v180, s[94:95]
	global_store_short_d16_hi v185, v181, s[94:95]
	s_waitcnt vmcnt(0)
	v_fmac_f32_e32 v139, v136, v138
	v_fmac_f32_e32 v147, v144, v146
	v_fmac_f32_e32 v155, v152, v154
	v_fmac_f32_e32 v163, v160, v162
	v_add_f32_dpp v178, v139, v139 quad_perm:[1,0,3,2] row_mask:0xf bank_mask:0xf bound_ctrl:1
	v_add_f32_dpp v179, v147, v147 quad_perm:[1,0,3,2] row_mask:0xf bank_mask:0xf bound_ctrl:1
	v_add_f32_dpp v180, v155, v155 quad_perm:[1,0,3,2] row_mask:0xf bank_mask:0xf bound_ctrl:1
	v_add_f32_dpp v181, v163, v163 quad_perm:[1,0,3,2] row_mask:0xf bank_mask:0xf bound_ctrl:1
	v_add_f32_dpp v178, v178, v178 quad_perm:[2,3,0,1] row_mask:0xf bank_mask:0xf bound_ctrl:1
	v_add_f32_dpp v179, v179, v179 quad_perm:[2,3,0,1] row_mask:0xf bank_mask:0xf bound_ctrl:1
	v_add_f32_dpp v180, v180, v180 quad_perm:[2,3,0,1] row_mask:0xf bank_mask:0xf bound_ctrl:1
	v_add_f32_dpp v181, v181, v181 quad_perm:[2,3,0,1] row_mask:0xf bank_mask:0xf bound_ctrl:1
	v_add_f32_dpp v178, v178, v178 row_half_mirror row_mask:0xf bank_mask:0xf bound_ctrl:1
	v_add_f32_dpp v179, v179, v179 row_half_mirror row_mask:0xf bank_mask:0xf bound_ctrl:1
	v_add_f32_dpp v180, v180, v180 row_half_mirror row_mask:0xf bank_mask:0xf bound_ctrl:1
	v_add_f32_dpp v181, v181, v181 row_half_mirror row_mask:0xf bank_mask:0xf bound_ctrl:1
	v_add_f32_dpp v178, v178, v178 row_mirror row_mask:0xf bank_mask:0xf bound_ctrl:1
	v_add_f32_dpp v179, v179, v179 row_mirror row_mask:0xf bank_mask:0xf bound_ctrl:1
	v_add_f32_dpp v180, v180, v180 row_mirror row_mask:0xf bank_mask:0xf bound_ctrl:1
	v_add_f32_dpp v181, v181, v181 row_mirror row_mask:0xf bank_mask:0xf bound_ctrl:1
	v_mov_b32_e32 v182, v65
	v_mov_b32_e32 v183, v65
	v_mov_b32_e32 v184, v65
	v_mov_b32_e32 v185, v65
	v_mov_b32_dpp v182, v178 row_bcast:15 row_mask:0xa bank_mask:0xf
	v_mov_b32_dpp v183, v179 row_bcast:15 row_mask:0xa bank_mask:0xf
	v_mov_b32_dpp v184, v180 row_bcast:15 row_mask:0xa bank_mask:0xf
	v_mov_b32_dpp v185, v181 row_bcast:15 row_mask:0xa bank_mask:0xf
	v_add_f32_e32 v178, v178, v182
	v_add_f32_e32 v179, v179, v183
	v_add_f32_e32 v180, v180, v184
	v_add_f32_e32 v181, v181, v185
	v_mov_b32_e32 v182, v65
	v_mov_b32_e32 v183, v65
	v_mov_b32_e32 v184, v65
	v_mov_b32_e32 v185, v65
	v_mov_b32_dpp v182, v178 row_bcast:31 row_mask:0xc bank_mask:0xf
	v_mov_b32_dpp v183, v179 row_bcast:31 row_mask:0xc bank_mask:0xf
	v_mov_b32_dpp v184, v180 row_bcast:31 row_mask:0xc bank_mask:0xf
	v_mov_b32_dpp v185, v181 row_bcast:31 row_mask:0xc bank_mask:0xf
	v_add_f32_e32 v178, v178, v182
	v_add_f32_e32 v179, v179, v183
	v_add_f32_e32 v180, v180, v184
	v_add_f32_e32 v181, v181, v185
	v_readlane_b32 s0, v178, 63
	v_readlane_b32 s1, v179, 63
	v_readlane_b32 s2, v180, 63
	v_readlane_b32 s20, v181, 63
	v_lshlrev_b32_e32 v140, 16, v140
	v_lshlrev_b32_e32 v148, 16, v148
	v_lshlrev_b32_e32 v156, 16, v156
	v_lshlrev_b32_e32 v164, 16, v164
	v_fmac_f32_e32 v139, s0, v193
	v_fmac_f32_e32 v147, s1, v193
	v_fmac_f32_e32 v155, s2, v193
	v_fmac_f32_e32 v163, s20, v193
	v_mul_f32_e32 v178, v139, v139
	v_mul_f32_e32 v179, v147, v147
	v_mul_f32_e32 v180, v155, v155
	v_mul_f32_e32 v181, v163, v163
	v_mov_b32_e32 v182, v65
	v_mov_b32_e32 v183, v65
	v_mov_b32_e32 v184, v65
	v_mov_b32_e32 v185, v65
	v_mov_b32_dpp v182, v178 quad_perm:[1,0,3,2] row_mask:0xf bank_mask:0xf
	v_mov_b32_dpp v183, v179 quad_perm:[1,0,3,2] row_mask:0xf bank_mask:0xf
	v_mov_b32_dpp v184, v180 quad_perm:[1,0,3,2] row_mask:0xf bank_mask:0xf
	v_mov_b32_dpp v185, v181 quad_perm:[1,0,3,2] row_mask:0xf bank_mask:0xf
	v_fmac_f32_e32 v182, v139, v139
	v_fmac_f32_e32 v183, v147, v147
	v_fmac_f32_e32 v184, v155, v155
	v_fmac_f32_e32 v185, v163, v163
	v_mov_b32_e32 v178, v182
	v_mov_b32_e32 v179, v183
	v_mov_b32_e32 v180, v184
	v_mov_b32_e32 v181, v185
	v_add_f32_dpp v178, v178, v178 quad_perm:[2,3,0,1] row_mask:0xf bank_mask:0xf bound_ctrl:1
	v_add_f32_dpp v179, v179, v179 quad_perm:[2,3,0,1] row_mask:0xf bank_mask:0xf bound_ctrl:1
	v_add_f32_dpp v180, v180, v180 quad_perm:[2,3,0,1] row_mask:0xf bank_mask:0xf bound_ctrl:1
	v_add_f32_dpp v181, v181, v181 quad_perm:[2,3,0,1] row_mask:0xf bank_mask:0xf bound_ctrl:1
	v_add_f32_dpp v178, v178, v178 row_half_mirror row_mask:0xf bank_mask:0xf bound_ctrl:1
	v_add_f32_dpp v179, v179, v179 row_half_mirror row_mask:0xf bank_mask:0xf bound_ctrl:1
	v_add_f32_dpp v180, v180, v180 row_half_mirror row_mask:0xf bank_mask:0xf bound_ctrl:1
	v_add_f32_dpp v181, v181, v181 row_half_mirror row_mask:0xf bank_mask:0xf bound_ctrl:1
	v_add_f32_dpp v178, v178, v178 row_mirror row_mask:0xf bank_mask:0xf bound_ctrl:1
	v_add_f32_dpp v179, v179, v179 row_mirror row_mask:0xf bank_mask:0xf bound_ctrl:1
	v_add_f32_dpp v180, v180, v180 row_mirror row_mask:0xf bank_mask:0xf bound_ctrl:1
	v_add_f32_dpp v181, v181, v181 row_mirror row_mask:0xf bank_mask:0xf bound_ctrl:1
	v_mov_b32_e32 v182, v65
	v_mov_b32_e32 v183, v65
	v_mov_b32_e32 v184, v65
	v_mov_b32_e32 v185, v65
	v_mov_b32_dpp v182, v178 row_bcast:15 row_mask:0xa bank_mask:0xf
	v_mov_b32_dpp v183, v179 row_bcast:15 row_mask:0xa bank_mask:0xf
	v_mov_b32_dpp v184, v180 row_bcast:15 row_mask:0xa bank_mask:0xf
	v_mov_b32_dpp v185, v181 row_bcast:15 row_mask:0xa bank_mask:0xf
	v_add_f32_e32 v178, v178, v182
	v_add_f32_e32 v179, v179, v183
	v_add_f32_e32 v180, v180, v184
	v_add_f32_e32 v181, v181, v185
	v_mov_b32_e32 v182, v65
	v_mov_b32_e32 v183, v65
	v_mov_b32_e32 v184, v65
	v_mov_b32_e32 v185, v65
	v_mov_b32_dpp v182, v178 row_bcast:31 row_mask:0xc bank_mask:0xf
	v_mov_b32_dpp v183, v179 row_bcast:31 row_mask:0xc bank_mask:0xf
	v_mov_b32_dpp v184, v180 row_bcast:31 row_mask:0xc bank_mask:0xf
	v_mov_b32_dpp v185, v181 row_bcast:31 row_mask:0xc bank_mask:0xf
	v_add_f32_e32 v178, v178, v182
	v_add_f32_e32 v179, v179, v183
	v_add_f32_e32 v180, v180, v184
	v_add_f32_e32 v181, v181, v185
	v_readlane_b32 s0, v178, 63
	v_readlane_b32 s1, v179, 63
	v_readlane_b32 s2, v180, 63
	v_readlane_b32 s20, v181, 63
	v_mul_f32_e32 v182, 0xbfb8aa3b, v140
	v_mul_f32_e32 v183, 0xbfb8aa3b, v148
	v_mul_f32_e32 v184, 0xbfb8aa3b, v156
	v_mul_f32_e32 v185, 0xbfb8aa3b, v164
	v_fma_f32 v178, s0, v194, v189
	v_fma_f32 v179, s1, v194, v189
	v_fma_f32 v180, s2, v194, v189
	v_fma_f32 v181, s20, v194, v189
	v_exp_f32_e32 v182, v182
	v_exp_f32_e32 v183, v183
	v_exp_f32_e32 v184, v184
	v_exp_f32_e32 v185, v185
	v_rsq_f32_e32 v178, v178
	v_rsq_f32_e32 v179, v179
	v_rsq_f32_e32 v180, v180
	v_rsq_f32_e32 v181, v181
	v_add_f32_e32 v182, 1.0, v182
	v_add_f32_e32 v183, 1.0, v183
	v_add_f32_e32 v184, 1.0, v184
	v_add_f32_e32 v185, 1.0, v185
	v_mul_f32_e32 v178, v139, v178
	v_mul_f32_e32 v179, v147, v179
	v_mul_f32_e32 v180, v155, v180
	v_mul_f32_e32 v181, v163, v181
	v_rcp_f32_e32 v182, v182
	v_rcp_f32_e32 v183, v183
	v_rcp_f32_e32 v184, v184
	v_rcp_f32_e32 v185, v185
	v_fma_f32 v178, v42, v178, v43
	v_fma_f32 v179, v42, v179, v43
	v_fma_f32 v180, v42, v180, v43
	v_fma_f32 v181, v42, v181, v43
	v_fmac_f32_e32 v178, v134, v138
	v_fmac_f32_e32 v179, v142, v146
	v_fmac_f32_e32 v180, v150, v154
	v_fmac_f32_e32 v181, v158, v162
	v_mul_f32_e32 v182, v182, v140
	v_mul_f32_e32 v183, v183, v148
	v_mul_f32_e32 v184, v184, v156
	v_mul_f32_e32 v185, v185, v164
	v_mul_f32_e32 v178, v182, v178
	v_mul_f32_e32 v179, v183, v179
	v_mul_f32_e32 v180, v184, v180
	v_mul_f32_e32 v181, v185, v181
	v_bfe_u32 v182, v178, 16, 1
	v_bfe_u32 v183, v179, 16, 1
	v_bfe_u32 v184, v180, 16, 1
	v_bfe_u32 v185, v181, 16, 1
	v_add3_u32 v178, v178, v182, s27
	v_add3_u32 v179, v179, v183, s27
	v_add3_u32 v180, v180, v184, s27
	v_add3_u32 v181, v181, v185, s27
	s_add_i32 s0, s28, 12
	s_lshl_b32 s0, s0, 11
	v_add_u32_e32 v182, s0, v176
	s_add_i32 s0, s28, 13
	s_lshl_b32 s0, s0, 11
	v_add_u32_e32 v183, s0, v176
	s_add_i32 s0, s28, 14
	s_lshl_b32 s0, s0, 11
	v_add_u32_e32 v184, s0, v176
	s_add_i32 s0, s28, 15
	s_lshl_b32 s0, s0, 11
	v_add_u32_e32 v185, s0, v176
	global_store_short_d16_hi v182, v178, s[94:95]
	global_store_short_d16_hi v183, v179, s[94:95]
	global_store_short_d16_hi v184, v180, s[94:95]
	global_store_short_d16_hi v185, v181, s[94:95]
	s_branch .LBB0_227
